# hand-written 2-level grid barrier: XCD-last releases, all WGs poll TOP (removes TOPGEN/XGEN hops, division)
# speedup vs baseline: 1.0031x; 1.0031x over previous
; #define LAS __attribute__((address_space(3)))
; __device__ __forceinline__ unsigned xb_add(unsigned* p, unsigned v) { return __hip_atomic_fetch_add(p, v, __ATOMIC_RELAXED, __HIP_MEMORY_SCOPE_AGENT); }
; __device__ __forceinline__ unsigned xb_xcc_id() { return (unsigned)__builtin_amdgcn_s_getreg((3 << 11) | 20) & 0xFu; }
; __device__ __forceinline__ XcdBarrier xcd_barrier_post(unsigned* bar, volatile LAS unsigned* st) {
;     XcdBarrier b; b.bar = bar; b.x = xb_xcc_id(); b.st = st;
;     if (threadIdx.x == 0) (void)xb_add(&bar[XB_XCNT(b.x)], 1u);
;     return b;
; }
; __global__ void __launch_bounds__(NTHREADS, 2) fwd_kernel(Params P) {
;     extern __shared__ __attribute__((aligned(16))) unsigned char lds_raw[];
;     LAS unsigned char* lds = (LAS unsigned char*)lds_raw;
;     volatile LAS unsigned* MISC = (volatile LAS unsigned*)(lds + MISC_OFF);
;     const int tid = threadIdx.x, lane = tid & 63; const int wave = __builtin_amdgcn_readfirstlane(tid >> 6);
;     const int G = gridDim.x, bx = blockIdx.x;
;     unsigned char* ws = P.ws; float* out = P.out; unsigned char* outb = (unsigned char*)P.out;
;     for (int u = tid; u < (LDS_BYTES - RING_BYTES) / 4; u += NTHREADS) ((LAS unsigned*)(lds + RING_BYTES))[u] = 0u;
;     __syncthreads();
;     const bool use_bar = (P.ph_hi - P.ph_lo) > 1;
;     XcdBarrier bar; bar.bar = (unsigned*)(ws + WS_CTL); bar.x = 0; bar.st = nullptr;
;     if (use_bar) bar = xcd_barrier_post((unsigned*)(ws + WS_CTL), MISC + 8);
;     const int lo = P.ph_lo, hi = P.ph_hi;
_Z10fwd_kernel6Params:
	s_load_dword s71, s[0:1], 0xd0
	s_add_u32 s4, s0, 0xd0
	s_addc_u32 s5, s1, 0
	v_lshl_add_u32 v1, v0, 2, 0
	v_mov_b32_e32 v253, 0
	v_writelane_b32 v252, s4, 0
	v_add_u32_e32 v2, 0x20000, v1
	v_mov_b32_e32 v3, 0
	v_readfirstlane_b32 s3, v0
	v_writelane_b32 v252, s5, 1
	ds_write2st64_b32 v2, v3, v3 offset1:8
	ds_write2st64_b32 v2, v3, v3 offset0:16 offset1:24
	v_or_b32_e32 v2, 0x800, v0
	s_mov_b64 s[4:5], -1
	s_and_saveexec_b64 s[6:7], s[4:5]
	v_lshl_add_u32 v4, v2, 2, 0
	v_add_u32_e32 v4, 0x20000, v4
	ds_write_b32 v4, v3
	s_or_b64 exec, exec, s[6:7]
	s_and_saveexec_b64 s[6:7], s[4:5]
	s_add_i32 s4, 0, 0x20000
	v_lshl_add_u32 v2, v2, 2, s4
	v_mov_b32_e32 v3, 0
	ds_write_b32 v2, v3 offset:2048
	s_or_b64 exec, exec, s[6:7]
	s_load_dwordx2 s[94:95], s[0:1], 0xc8
	v_or_b32_e32 v2, 0xc00, v0
	v_cmp_gt_u32_e64 s[4:5], 7, 6
	v_cmp_gt_u32_e64 s[8:9], 7, 5
	s_and_saveexec_b64 s[6:7], s[8:9]
	v_lshl_add_u32 v3, v2, 2, 0
	v_add_u32_e32 v3, 0x20000, v3
	v_mov_b32_e32 v4, 0
	ds_write_b32 v3, v4
	s_or_b64 exec, exec, s[6:7]
	s_load_dwordx2 s[68:69], s[0:1], 0xc0
	s_and_saveexec_b64 s[6:7], s[4:5]
	s_add_i32 s4, 0, 0x20000
	v_lshl_add_u32 v2, v2, 2, s4
	v_mov_b32_e32 v3, 0
	ds_write_b32 v2, v3 offset:2048
	s_or_b64 exec, exec, s[6:7]
	s_load_dwordx16 s[8:23], s[0:1], 0x0
	s_load_dwordx16 s[52:67], s[0:1], 0x40
	s_load_dwordx16 s[36:51], s[0:1], 0x80
	s_waitcnt lgkmcnt(0)
	s_sub_i32 s0, s95, s94
	s_mov_b32 s1, 0
	s_cmp_lt_i32 s0, 2
	v_cmp_eq_u32_e32 vcc, 0, v0
	s_mov_b32 s91, 0
	s_barrier
	v_writelane_b32 v252, s1, 2
	s_cbranch_scc1 .LBB0_13
	s_getreg_b32 s0, hwreg(HW_REG_XCC_ID, 0, 4)
	s_and_b32 s0, s0, 15
	v_writelane_b32 v252, s0, 2
	s_and_saveexec_b64 s[0:1], vcc
	s_cbranch_execz .LBB0_12
	s_mov_b64 s[4:5], exec
	v_mbcnt_lo_u32_b32 v2, s4, 0
	v_mbcnt_hi_u32_b32 v2, s5, v2
	v_cmp_eq_u32_e32 vcc, 0, v2
	s_and_b64 s[6:7], exec, vcc
	s_mov_b64 exec, s[6:7]
	s_cbranch_execz .LBB0_12
	v_readlane_b32 s6, v252, 2
	s_lshl_b32 s6, s6, 8
	s_bcnt1_i32_b64 s4, s[4:5]
	v_mov_b32_e32 v2, s6
	v_mov_b32_e32 v3, s4
	global_atomic_add v2, v3, s[68:69] offset:1024

; __device__ __forceinline__ unsigned xb_ld(unsigned* p)              { return __hip_atomic_load(p, __ATOMIC_RELAXED, __HIP_MEMORY_SCOPE_AGENT); }
; __device__ __forceinline__ unsigned xb_add(unsigned* p, unsigned v) { return __hip_atomic_fetch_add(p, v, __ATOMIC_RELAXED, __HIP_MEMORY_SCOPE_AGENT); }
;     __device__ __forceinline__ bool next(int i, Unit& u) const {
;         const long L = (long)(i >> psh) * G + c; if (L >= nwg) return false;
;         int wgid = (int)L; { const int q = nwg / NXCD, r = nwg % NXCD, xcd = wgid % NXCD, off = wgid / NXCD; wgid = (xcd < r ? xcd * (q + 1) : r * (q + 1) + (xcd - r) * q) + off; }
;         const int nig = WGM * nN, gid = wgid / nig, fm = gid * WGM, gsz = (nM - fm) < WGM ? (nM - fm) : WGM;
;         u.pm = fm + ((wgid % nig) % gsz); u.pn = (wgid % nig) / gsz; u.part = i & ((1 << psh) - 1); u.idx = i; return true;
; __device__ __forceinline__ void xcd_barrier(const XcdBarrier& b) {
;     asm volatile("s_waitcnt vmcnt(0)" ::: "memory");
;     __syncthreads();
;     if (threadIdx.x == 0) {
;         unsigned* bar = b.bar;
;         __builtin_amdgcn_s_waitcnt(0);
;         unsigned nloc = b.st[0], nx = b.st[1];
;         if (nloc == 0u) { xcd_barrier_complete(bar, b.x, nloc, nx); b.st[0] = nloc; b.st[1] = nx; }
;         const unsigned old = xb_add(&bar[XB_XSUB(b.x)], 1u);
;         const unsigned gen = old / nloc;
;         if (old + 1u == (gen + 1u) * nloc) {
;             __builtin_amdgcn_fence(__ATOMIC_RELEASE, "agent");
;             asm volatile("s_waitcnt vmcnt(0)" ::: "memory");
;             const unsigned og = xb_add(&bar[XB_TOP], 1u);
;             const unsigned tg = og / nx;
;             if (og + 1u == (tg + 1u) * nx) xb_add(&bar[XB_TOPGEN], 1u);
;             else XB_SPIN(xb_ld(&bar[XB_TOPGEN]) == tg, bar);
;             __builtin_amdgcn_fence(__ATOMIC_ACQUIRE, "agent");
;             xb_add(&bar[XB_XGEN(b.x)], 1u);
;             asm volatile("s_waitcnt vmcnt(0)" ::: "memory");
;         } else {
;             XB_SPIN(xb_ld(&bar[XB_XGEN(b.x)]) == gen, bar);
;             __builtin_amdgcn_fence(__ATOMIC_ACQUIRE, "agent");
;             asm volatile("s_waitcnt vmcnt(0)" ::: "memory");
;         }
;     }
;     __syncthreads();
; }
.LBB0_262:
	s_cmp_gt_i32 s95, 1
	s_cselect_b64 s[0:1], -1, 0
	s_and_b64 s[4:5], s[4:5], s[0:1]
	s_andn2_b64 vcc, exec, s[4:5]
	s_cbranch_vccnz .LBB0_312
	s_waitcnt vmcnt(0) lgkmcnt(0)
	s_barrier
	v_readfirstlane_b32 s98, v0
	s_cmp_lg_u32 s98, 0
	s_cbranch_scc1 .Lxb0_end
	s_mov_b64 s[100:101], exec
	v_readlane_b32 s98, v253, 0
	s_cmp_lg_u32 s98, 0
	s_cbranch_scc1 .Lxb0_have
	s_mov_b64 exec, 0xffff
	v_mbcnt_lo_u32_b32 v254, -1, 0
	v_lshlrev_b32_e32 v254, 8, v254
	s_mov_b32 s99, 0
	v_writelane_b32 v253, s99, 3
.Lxb0_cpoll:
	global_load_dword v255, v254, s[68:69] offset:1024 sc1
	s_waitcnt vmcnt(0)
	v_cmp_ne_u32_e32 vcc, 0, v255
	s_nop 1
	s_bcnt1_i32_b64 s99, vcc
	s_mov_b32 s98, 0
	v_readlane_b32 vcc_lo, v255, 0
	s_add_u32 s98, s98, vcc_lo
	v_readlane_b32 vcc_lo, v255, 1
	s_add_u32 s98, s98, vcc_lo
	v_readlane_b32 vcc_lo, v255, 2
	s_add_u32 s98, s98, vcc_lo
	v_readlane_b32 vcc_lo, v255, 3
	s_add_u32 s98, s98, vcc_lo
	v_readlane_b32 vcc_lo, v255, 4
	s_add_u32 s98, s98, vcc_lo
	v_readlane_b32 vcc_lo, v255, 5
	s_add_u32 s98, s98, vcc_lo
	v_readlane_b32 vcc_lo, v255, 6
	s_add_u32 s98, s98, vcc_lo
	v_readlane_b32 vcc_lo, v255, 7
	s_add_u32 s98, s98, vcc_lo
	v_readlane_b32 vcc_lo, v255, 8
	s_add_u32 s98, s98, vcc_lo
	v_readlane_b32 vcc_lo, v255, 9
	s_add_u32 s98, s98, vcc_lo
	v_readlane_b32 vcc_lo, v255, 10
	s_add_u32 s98, s98, vcc_lo
	v_readlane_b32 vcc_lo, v255, 11
	s_add_u32 s98, s98, vcc_lo
	v_readlane_b32 vcc_lo, v255, 12
	s_add_u32 s98, s98, vcc_lo
	v_readlane_b32 vcc_lo, v255, 13
	s_add_u32 s98, s98, vcc_lo
	v_readlane_b32 vcc_lo, v255, 14
	s_add_u32 s98, s98, vcc_lo
	v_readlane_b32 vcc_lo, v255, 15
	s_add_u32 s98, s98, vcc_lo
	s_cmp_eq_u32 s98, s71
	s_cbranch_scc1 .Lxb0_cdone
	s_sleep 2
	v_readlane_b32 s98, v253, 3
	s_add_u32 s98, s98, 1
	v_writelane_b32 v253, s98, 3
	s_cmp_lt_u32 s98, 0x4000
	s_cbranch_scc1 .Lxb0_cpoll
.Lxb0_cdone:
	s_max_u32 s99, s99, 1
	v_writelane_b32 v253, s99, 1
	v_readlane_b32 s99, v252, 2
	s_nop 3
	v_readlane_b32 s98, v255, s99
	s_nop 0
	s_max_u32 s98, s98, 1
	v_writelane_b32 v253, s98, 0
.Lxb0_have:
	s_mov_b64 exec, 1
	v_readlane_b32 s99, v252, 2
	s_lshl_b32 s99, s99, 8
	s_add_u32 s99, s99, 0x1400
	v_mov_b32_e32 v254, s99
	v_mov_b32_e32 v255, 1
	global_atomic_add v255, v254, v255, s[68:69] sc0
	v_readlane_b32 s99, v253, 2
	s_add_u32 s99, s99, 1
	v_writelane_b32 v253, s99, 2
	s_mul_i32 s98, s98, s99
	s_waitcnt vmcnt(0)
	v_readfirstlane_b32 vcc_lo, v255
	s_add_u32 vcc_lo, vcc_lo, 1
	s_cmp_lg_u32 vcc_lo, s98
	s_cbranch_scc1 .Lxb0_wait
	buffer_wbl2 sc1
	s_waitcnt vmcnt(0)
	v_mov_b32_e32 v254, 0x3400
	v_mov_b32_e32 v255, 1
	global_atomic_add v254, v255, s[68:69]
.Lxb0_wait:
	v_readlane_b32 s98, v253, 1
	s_mul_i32 s98, s98, s99
	v_mov_b32_e32 v254, 0x3400
	s_mov_b32 s99, 0
.Lxb0_spin:
	global_load_dword v255, v254, s[68:69] sc1
	s_waitcnt vmcnt(0)
	v_readfirstlane_b32 vcc_lo, v255
	s_cmp_ge_u32 vcc_lo, s98
	s_cbranch_scc1 .Lxb0_done
	s_sleep 1
	s_add_u32 s99, s99, 1
	s_cmp_lt_u32 s99, 0x4000
	s_cbranch_scc1 .Lxb0_spin
.Lxb0_done:
	buffer_inv sc1
	s_waitcnt vmcnt(0)
	s_mov_b64 exec, s[100:101]
.Lxb0_end:
	s_barrier
.LBB0_312:
	s_cmp_lt_i32 s94, 2
	s_cselect_b64 s[4:5], -1, 0
	s_add_u32 s88, s68, 0x580000
	s_addc_u32 s89, s69, 0
	s_add_u32 s80, s68, 0x4680000
	s_addc_u32 s81, s69, 0
	s_and_b64 s[10:11], s[4:5], s[0:1]
	s_andn2_b64 vcc, exec, s[10:11]
	v_lshrrev_b32_e32 v199, 8, v0
	v_writelane_b32 v252, s88, 16
	s_nop 1
	v_writelane_b32 v252, s89, 17
	s_cbranch_vccnz .LBB0_591
	s_ashr_i32 s3, s2, 31
	s_waitcnt vmcnt(15)
	v_mov_b64_e32 v[2:3], s[2:3]
	v_mad_i64_i32 v[2:3], s[0:1], v199, s71, v[2:3]
	s_mov_b64 s[0:1], 0x596
	s_ashr_i32 s33, s71, 31
	v_cmp_gt_i64_e32 vcc, s[0:1], v[2:3]
	v_mov_b32_e32 v3, 0
	s_and_saveexec_b64 s[4:5], vcc
	s_cbranch_execz .LBB0_319
	v_ashrrev_i32_e32 v3, 31, v2
	v_lshrrev_b32_e32 v3, 29, v3
	v_add_u32_e32 v4, v2, v3
	v_and_b32_e32 v3, -8, v4
	v_sub_u32_e32 v3, v2, v3
	v_cmp_lt_i32_e64 s[0:1], 5, v3
	s_and_saveexec_b64 s[6:7], s[0:1]
	s_xor_b64 s[0:1], exec, s[6:7]
	s_movk_i32 s6, 0xb2
	v_mad_u64_u32 v[2:3], s[6:7], v3, s6, 6
	s_or_saveexec_b64 s[0:1], s[0:1]
	v_ashrrev_i32_e32 v4, 3, v4
	s_xor_b64 exec, exec, s[0:1]
	s_movk_i32 s6, 0xb3
	v_mul_lo_u32 v2, v3, s6
	s_or_b64 exec, exec, s[0:1]
	v_add_u32_e32 v2, v2, v4
	s_mov_b32 s0, 0x2e8ba2e9
	v_mul_hi_i32 v3, v2, s0
	v_lshrrev_b32_e32 v4, 31, v3
	v_ashrrev_i32_e32 v3, 4, v3
	v_add_u32_e32 v3, v3, v4
	v_lshlrev_b32_e32 v4, 2, v3
	v_sub_u32_e32 v5, 0x41, v4
	v_min_i32_e32 v5, 4, v5
	s_waitcnt vmcnt(14)
	v_sub_u32_e32 v6, 0, v5
	v_max_i32_e32 v5, v5, v6
	v_cvt_f32_u32_e32 v6, v5
	s_movk_i32 s0, 0x58
	v_mul_lo_u32 v3, v3, s0
	v_sub_u32_e32 v2, v2, v3
	v_rcp_iflag_f32_e32 v6, v6
	v_sub_u32_e32 v7, 0, v2
	v_ashrrev_i32_e32 v3, 31, v2
	v_max_i32_e32 v2, v2, v7
	v_mul_f32_e32 v6, 0x4f7ffffe, v6
	v_cvt_u32_f32_e32 v6, v6
	v_sub_u32_e32 v7, 0, v5
	v_mul_lo_u32 v7, v7, v6
	v_mul_hi_u32 v7, v6, v7
	v_add_u32_e32 v6, v6, v7
	v_mul_hi_u32 v6, v2, v6
	v_mul_lo_u32 v6, v6, v5
	v_sub_u32_e32 v2, v2, v6
	v_sub_u32_e32 v6, v2, v5
	v_cmp_ge_u32_e64 s[0:1], v2, v5
	s_nop 1
	v_cndmask_b32_e64 v2, v2, v6, s[0:1]
	v_sub_u32_e32 v6, v2, v5
	v_cmp_ge_u32_e64 s[0:1], v2, v5
	s_nop 1
	v_cndmask_b32_e64 v2, v2, v6, s[0:1]
	v_xor_b32_e32 v2, v2, v3
	v_sub_u32_e32 v2, v2, v3
	v_add_lshl_u32 v3, v4, v2, 8

; __device__ __forceinline__ void xcd_barrier(const XcdBarrier& b) {
;     asm volatile("s_waitcnt vmcnt(0)" ::: "memory");
;     __syncthreads();
;     if (threadIdx.x == 0) {
;         unsigned* bar = b.bar;
;         __builtin_amdgcn_s_waitcnt(0);
;         unsigned nloc = b.st[0], nx = b.st[1];
;         if (nloc == 0u) { xcd_barrier_complete(bar, b.x, nloc, nx); b.st[0] = nloc; b.st[1] = nx; }
.LBB0_591:
	s_cmp_gt_i32 s95, 2
	s_cselect_b64 s[0:1], -1, 0
	s_and_b64 s[4:5], s[10:11], s[0:1]
	s_andn2_b64 vcc, exec, s[4:5]
	s_cbranch_vccnz .LBB0_641
	s_waitcnt vmcnt(0) lgkmcnt(0)
	s_barrier
	v_readfirstlane_b32 s98, v0
	s_cmp_lg_u32 s98, 0
	s_cbranch_scc1 .Lxb1_end
	s_mov_b64 s[100:101], exec
	v_readlane_b32 s98, v253, 0
	s_cmp_lg_u32 s98, 0
	s_cbranch_scc1 .Lxb1_have
	s_mov_b64 exec, 0xffff
	v_mbcnt_lo_u32_b32 v254, -1, 0
	v_lshlrev_b32_e32 v254, 8, v254
	s_mov_b32 s99, 0
	v_writelane_b32 v253, s99, 3

; __global__ void __launch_bounds__(NTHREADS, 2) fwd_kernel(Params P) {
;     ...
;     const bool stagger = (G == 256);
;     const bool sk_early = stagger && ((bx >> 3) & 1) == 0;
;     const int sk_piece = stagger ? (((bx >> 3) & 15) * 16 + 2 * (bx & 7) + (bx >> 7)) : bx;
;     if (IN(2)) {
;         pg8::Gemm g{Hb, Wdn1, FF, FF, FF, 0}; pg8::Sched S; S.init(MP, D, G, bx, 0);
;         pg8::EpiResidual<true, false, true> E{XA, nullptr, nullptr, XA, ssq1, 0.5f};
;         skinny::EpiResidual<true, false, true> Es{XA, nullptr, XA, 0.5f};
;         if (sk_early) skinny::phase<1, FF / 256, false>(lds, Hb, FF, Wdn1, FF, 0, ssq1, G, sk_piece, Es);
;         pg8::gemm_phase(lds, g, S, E);
;         if (!sk_early) skinny::phase<1, FF / 256, false>(lds, Hb, FF, Wdn1, FF, 0, ssq1, G, sk_piece, Es);
.Lxb1_end:
	s_barrier
.LBB0_641:
	s_cmp_lt_i32 s94, 3
	s_cselect_b64 s[4:5], -1, 0
	s_add_u32 s22, s68, 0x114000
	s_addc_u32 s23, s69, 0
	s_cmpk_lg_i32 s71, 0x100
	s_cselect_b64 s[72:73], -1, 0
	s_bitcmp1_b32 s2, 3
	s_cselect_b64 s[6:7], -1, 0
	s_or_b64 s[6:7], s[6:7], s[72:73]
	v_writelane_b32 v252, s6, 18
	s_lshl_b32 s3, s2, 1
	s_nop 0
	v_writelane_b32 v252, s7, 19
	v_writelane_b32 v252, s3, 20
	s_and_b32 s3, s3, 0xfe
	s_ashr_i32 s6, s2, 7
	s_add_i32 s3, s3, s6
	s_cmpk_eq_i32 s71, 0x100
	s_cselect_b64 s[6:7], -1, 0
	v_writelane_b32 v252, s6, 21
	s_nop 1
	v_writelane_b32 v252, s7, 22
	s_and_b64 s[6:7], s[6:7], exec
	v_writelane_b32 v252, s3, 23
	s_cselect_b32 s3, s3, s2
	s_and_b64 s[10:11], s[4:5], s[0:1]
	s_andn2_b64 vcc, exec, s[10:11]
	v_writelane_b32 v252, s3, 24
	s_cbranch_vccnz .LBB0_710
	v_readlane_b32 s4, v252, 18
	v_readlane_b32 s5, v252, 19
	s_andn2_b64 vcc, exec, s[4:5]
	s_waitcnt vmcnt(0)
	v_cndmask_b32_e64 v2, 0, 1, s[4:5]
	v_cmp_ne_u32_e64 s[0:1], 1, v2
	s_cbranch_vccnz .LBB0_644
	v_lshrrev_b32_e32 v211, 2, v0
	v_and_b32_e32 v210, 15, v0
	s_cbranch_execz .LBB0_645
	s_branch .LBB0_654

; __device__ __forceinline__ void xcd_barrier(const XcdBarrier& b) {
;     asm volatile("s_waitcnt vmcnt(0)" ::: "memory");
;     __syncthreads();
;     if (threadIdx.x == 0) {
;         unsigned* bar = b.bar;
;         __builtin_amdgcn_s_waitcnt(0);
;         unsigned nloc = b.st[0], nx = b.st[1];
;         if (nloc == 0u) { xcd_barrier_complete(bar, b.x, nloc, nx); b.st[0] = nloc; b.st[1] = nx; }
.LBB0_710:
	s_cmp_gt_i32 s95, 3
	s_cselect_b64 s[0:1], -1, 0
	s_and_b64 s[4:5], s[10:11], s[0:1]
	s_andn2_b64 vcc, exec, s[4:5]
	s_cbranch_vccnz .LBB0_760
	s_waitcnt vmcnt(0) lgkmcnt(0)
	s_barrier
	v_readfirstlane_b32 s98, v0
	s_cmp_lg_u32 s98, 0
	s_cbranch_scc1 .Lxb2_end
	s_mov_b64 s[100:101], exec
	v_readlane_b32 s98, v253, 0
	s_cmp_lg_u32 s98, 0
	s_cbranch_scc1 .Lxb2_have
	s_mov_b64 exec, 0xffff
	v_mbcnt_lo_u32_b32 v254, -1, 0
	v_lshlrev_b32_e32 v254, 8, v254
	s_mov_b32 s99, 0
	v_writelane_b32 v253, s99, 3

;     __device__ __forceinline__ bool next(int i, Unit& u) const {
;         const long L = (long)(i >> psh) * G + c; if (L >= nwg) return false;
;         int wgid = (int)L; { const int q = nwg / NXCD, r = nwg % NXCD, xcd = wgid % NXCD, off = wgid / NXCD; wgid = (xcd < r ? xcd * (q + 1) : r * (q + 1) + (xcd - r) * q) + off; }
;         const int nig = WGM * nN, gid = wgid / nig, fm = gid * WGM, gsz = (nM - fm) < WGM ? (nM - fm) : WGM;
;         u.pm = fm + ((wgid % nig) % gsz); u.pn = (wgid % nig) / gsz; u.part = i & ((1 << psh) - 1); u.idx = i; return true;
; __global__ void __launch_bounds__(NTHREADS, 2) fwd_kernel(Params P) {
;     ...
;     if (IN(3)) {
;         pg8::Gemm g{XA, Win, D, D, D, 0}; pg8::Sched S; S.init(M, NIN_V, G, bx, 0);
;         RSTD_TABLE_FILL(S, ssq1, false);
.Lxb2_end:
	s_barrier
.LBB0_760:
	v_writelane_b32 v252, s91, 25
	v_writelane_b32 v252, s92, 26
	s_nop 1
	v_writelane_b32 v252, s93, 27
	v_writelane_b32 v252, s94, 28
	s_cmp_lt_i32 s94, 4
	s_cselect_b64 s[4:5], -1, 0
	s_add_u32 s96, s68, 0x420000
	s_addc_u32 s97, s69, 0
	s_add_u32 s40, s68, 0x2600000
	s_addc_u32 s41, s69, 0
	v_writelane_b32 v252, s95, 29
	s_add_u32 s94, s68, 0x6700000
	s_addc_u32 s95, s69, 0
	s_add_u32 s92, s68, 0xa800000
	s_addc_u32 s93, s69, 0
	s_add_u32 s74, s68, 0xe900000
	s_addc_u32 s75, s69, 0
	s_and_b64 s[38:39], s[4:5], s[0:1]
	s_andn2_b64 vcc, exec, s[38:39]
	s_cbranch_vccnz .LBB0_988
	s_ashr_i32 s3, s2, 31
	s_waitcnt vmcnt(0) lgkmcnt(0)
	v_mov_b64_e32 v[2:3], s[2:3]
	v_mad_i64_i32 v[2:3], s[0:1], v199, s71, v[2:3]
	s_mov_b64 s[0:1], 0x6db
	s_ashr_i32 s33, s71, 31
	v_cmp_gt_i64_e32 vcc, s[0:1], v[2:3]
	v_mov_b32_e32 v3, 0
	s_and_saveexec_b64 s[4:5], vcc
	s_cbranch_execz .LBB0_767
	v_ashrrev_i32_e32 v3, 31, v2
	v_lshrrev_b32_e32 v3, 29, v3
	v_add_u32_e32 v4, v2, v3
	v_and_b32_e32 v3, -8, v4
	v_sub_u32_e32 v3, v2, v3
	v_cmp_lt_i32_e64 s[0:1], 2, v3
	s_and_saveexec_b64 s[6:7], s[0:1]
	s_xor_b64 s[0:1], exec, s[6:7]
	s_movk_i32 s6, 0xdb
	v_mad_u64_u32 v[2:3], s[6:7], v3, s6, 3
	s_or_saveexec_b64 s[0:1], s[0:1]
	v_ashrrev_i32_e32 v4, 3, v4
	s_xor_b64 exec, exec, s[0:1]
	s_movk_i32 s6, 0xdc
	v_mul_lo_u32 v2, v3, s6
	s_or_b64 exec, exec, s[0:1]
	v_add_u32_e32 v2, v2, v4
	s_mov_b32 s0, 0x4bda12f7
	v_mul_hi_i32 v3, v2, s0
	v_lshrrev_b32_e32 v4, 31, v3
	v_ashrrev_i32_e32 v3, 5, v3
	v_add_u32_e32 v3, v3, v4
	v_lshlrev_b32_e32 v4, 2, v3
	v_sub_u32_e32 v5, 0x41, v4
	v_min_i32_e32 v5, 4, v5
	v_sub_u32_e32 v6, 0, v5
	v_max_i32_e32 v5, v5, v6
	v_cvt_f32_u32_e32 v6, v5
	s_movk_i32 s0, 0x6c
	v_mul_lo_u32 v3, v3, s0
	v_sub_u32_e32 v2, v2, v3
	v_rcp_iflag_f32_e32 v6, v6
	v_sub_u32_e32 v7, 0, v2
	v_ashrrev_i32_e32 v3, 31, v2
	v_max_i32_e32 v2, v2, v7
	v_mul_f32_e32 v6, 0x4f7ffffe, v6
	v_cvt_u32_f32_e32 v6, v6
	v_sub_u32_e32 v7, 0, v5
	v_mul_lo_u32 v7, v7, v6
	v_mul_hi_u32 v7, v6, v7
	v_add_u32_e32 v6, v6, v7
	v_mul_hi_u32 v6, v2, v6
	v_mul_lo_u32 v6, v6, v5
	v_sub_u32_e32 v2, v2, v6
	v_sub_u32_e32 v6, v2, v5
	v_cmp_ge_u32_e64 s[0:1], v2, v5
	s_nop 1
	v_cndmask_b32_e64 v2, v2, v6, s[0:1]
	v_sub_u32_e32 v6, v2, v5
	v_cmp_ge_u32_e64 s[0:1], v2, v5
	s_nop 1
	v_cndmask_b32_e64 v2, v2, v6, s[0:1]
	v_xor_b32_e32 v2, v2, v3
	v_sub_u32_e32 v2, v2, v3
	v_add_lshl_u32 v3, v4, v2, 8

; __device__ __forceinline__ void xcd_barrier(const XcdBarrier& b) {
;     asm volatile("s_waitcnt vmcnt(0)" ::: "memory");
;     __syncthreads();
;     if (threadIdx.x == 0) {
;         unsigned* bar = b.bar;
;         __builtin_amdgcn_s_waitcnt(0);
;         unsigned nloc = b.st[0], nx = b.st[1];
;         if (nloc == 0u) { xcd_barrier_complete(bar, b.x, nloc, nx); b.st[0] = nloc; b.st[1] = nx; }
.LBB0_988:
	v_readlane_b32 s0, v252, 28
	v_readlane_b32 s1, v252, 29
	s_cmp_gt_i32 s1, 4
	s_cselect_b64 s[0:1], -1, 0
	s_and_b64 s[4:5], s[38:39], s[0:1]
	s_andn2_b64 vcc, exec, s[4:5]
	s_cbranch_vccnz .LBB0_1038
	s_waitcnt vmcnt(0) lgkmcnt(0)
	s_barrier
	v_readfirstlane_b32 s98, v0
	s_cmp_lg_u32 s98, 0
	s_cbranch_scc1 .Lxb3_end
	s_mov_b64 s[100:101], exec
	v_readlane_b32 s98, v253, 0
	s_cmp_lg_u32 s98, 0
	s_cbranch_scc1 .Lxb3_have
	s_mov_b64 exec, 0xffff
	v_mbcnt_lo_u32_b32 v254, -1, 0
	v_lshlrev_b32_e32 v254, 8, v254
	s_mov_b32 s99, 0
	v_writelane_b32 v253, s99, 3

; #define LAS __attribute__((address_space(3)))
; template <bool FULL, bool PARTIAL  > ...
;     const int tid = threadIdx.x, lane = tid & 63, r = lane & 31, h = lane >> 5; const int w = __builtin_amdgcn_readfirstlane(tid >> 6);
;     const int kt = w & 3, tt = w >> 2, kk = 32 * kt + r;
;     const int nvalid = PARTIAL ? nvalid_ : 64;
;     LAS bf16_t* QS = (LAS bf16_t*)(lds + OFF_QS); LAS bf16_t* KS = (LAS bf16_t*)(lds + OFF_KS); LAS bf16_t* KdT = (LAS bf16_t*)(lds + OFF_KDT); LAS bf16_t* Ab = (LAS bf16_t*)(lds + OFF_A);
;     LAS bf16_t* VS = (LAS bf16_t*)(lds + OFF_VS); LAS float* GAs = (LAS float*)(lds + OFF_GA); LAS float* EB = (LAS float*)(lds + OFF_EB); LAS float* CS = (LAS float*)(lds + OFF_CS);
;     LAS float* PART = (LAS float*)(lds + OFF_PART);
;     float wal[8];
; #pragma unroll
;     for (int i = 0; i < 8; ++i) wal[i] = w_alpha[(2 * i + h) * 512 + hd * 128 + kk];
;     const float bal = b_alpha[hd * 128 + kk];
;     f32x16 Sacc[4];
;     float dsum = 0.f;
;     if (FULL && tid < 256) ((LAS float*)(lds + OFF_HN))[tid] = head_norm[tid];
;     f32x4 raw_ga; u32x4 raw_k[2], raw_q[2];
;     const int nv1 = nvalid - 1;
;     const u32x4 z4 = (u32x4){0u, 0u, 0u, 0u};
;     ...
;     GLA_FETCH_KG(0);
;     asm volatile("" :: "v"(raw_ga), "v"(raw_k[0]), "v"(raw_k[1]));
;     if (FULL) asm volatile("" :: "v"(raw_q[0]), "v"(raw_q[1]));
;     if (FULL && S0) {
;         const float* s0p = S0 + (size_t)(4 * h) * 256 + 32 * w + r;
; #pragma unroll
;         for (int kb = 0; kb < 4; ++kb)
; #pragma unroll
;             for (int i = 0; i < 16; ++i) Sacc[kb][i] = s0p[(32 * kb + (i & 3) + 8 * (i >> 2)) * 256];
;     } else {
; #pragma unroll
;         for (int kb = 0; kb < 4; ++kb)
; #pragma unroll
;             for (int i = 0; i < 16; ++i) Sacc[kb][i] = 0.f;
;     }
;     f32x16 oT[2]; u32x2 grv[2][4];
;     const LAS float* hn_r = opq((LAS float*)(lds + OFF_HN) + 32 * w + 4 * h);
;     LAS float* part_p = opq(PART + r);
; __global__ void __launch_bounds__(NTHREADS, 2) fwd_kernel(Params P) {
;     ...
;         for (int it = bx; it < 240; it += G) { const int bh = it / 15, sc = it % 15, b = bh >> 2, hd = bh & 3;
;             gla::span<false, false>(lds, b * SEQ + sc * 256, 4, 64, hd, QK, Vb, AB, GA, P.in[10], P.in[11], P.in[12], nullptr, DS + (size_t)it * 32768, DV + (size_t)it * 128); }
.Lxb3_end:
	s_barrier
.LBB0_1038:
	v_readlane_b32 s4, v252, 28
	v_readlane_b32 s5, v252, 29
	s_cmp_lt_i32 s4, 5
	s_cselect_b64 s[4:5], -1, 0
	s_add_u32 s8, s68, 0x524000
	s_addc_u32 s9, s69, 0
	s_and_b64 s[20:21], s[4:5], s[0:1]
	s_andn2_b64 vcc, exec, s[20:21]
	s_cbranch_vccnz .LBB0_1195
	s_cmpk_gt_i32 s2, 0xef
	s_cbranch_scc1 .LBB0_1060
	s_waitcnt vmcnt(0)
	v_lshrrev_b32_e32 v5, 4, v0
	s_movk_i32 s3, 0x110
	v_lshlrev_b32_e32 v6, 4, v0
	v_mad_u32_u24 v5, v5, s3, 0
	v_and_b32_e32 v7, 0xf0, v6
	s_movk_i32 s4, 0x4400
	v_add3_u32 v125, v5, v7, s4
	v_lshlrev_b32_e32 v5, 2, v0
	v_lshrrev_b32_e32 v2, 5, v198
	v_and_b32_e32 v5, 12, v5
	v_and_b32_e32 v114, 31, v0
	s_add_i32 s0, 0, 0x1a700
	s_waitcnt lgkmcnt(0)
	v_lshlrev_b32_e32 v3, 4, v2
	v_mul_u32_u24_e32 v7, 0x110, v5
	s_add_i32 s4, 0, 0x18400
	v_and_b32_e32 v8, 0x1fc, v0
	v_add_u32_e32 v123, s0, v3
	s_add_i32 s0, 0, 0x19f00
	v_lshlrev_b32_e32 v4, 2, v114
	v_add3_u32 v126, s4, v7, v8
	v_mul_u32_u24_e32 v7, 0x110, v2
	v_add_u32_e32 v124, s0, v4
	v_add3_u32 v127, s4, v7, v4
	v_lshrrev_b32_e32 v4, 5, v0
	s_movk_i32 s6, 0x240
	v_mad_u32_u24 v4, v4, s6, 0
	v_and_b32_e32 v6, 0x1f0, v6
	s_mov_b32 s10, 0xf400
	v_add3_u32 v128, v4, v6, s10
	s_movk_i32 s10, 0x90
	v_mad_u32_u24 v4, v114, s10, 0
	s_mov_b32 s18, 0x8800
	v_add3_u32 v129, v4, v3, s18
	v_bfe_u32 v4, v0, 2, 2
	v_lshl_or_b32 v4, v2, 3, v4
	v_and_b32_e32 v6, 16, v0
	s_add_i32 s19, 0, 0x19500
	v_lshlrev_b32_e32 v115, 9, v2
	v_lshlrev_b32_e32 v122, 2, v2
	s_movk_i32 s0, 0x100
	v_mad_u32_u24 v4, v4, s6, 0
	v_lshlrev_b32_e32 v6, 1, v6
	v_lshlrev_b32_e32 v5, 1, v5
	s_cmp_lg_u64 s[50:51], 0
	v_mov_b32_e32 v117, 0
	v_lshlrev_b32_e32 v118, 12, v2
	v_mbcnt_lo_u32_b32 v2, -1, 0
	s_mov_b32 s7, 0
	v_cmp_gt_u32_e64 s[0:1], s0, v0
	v_cmp_gt_u32_e64 s[4:5], 32, v198
	v_add3_u32 v130, v4, v6, v5
	v_add_u32_e32 v131, s19, v3
	s_cselect_b64 s[10:11], -1, 0
	v_mov_b32_e32 v119, v117
	s_movk_i32 s33, 0x2000
	s_movk_i32 s38, 0x4000
	s_movk_i32 s39, 0x6000
	s_add_i32 s42, 0, 0x19700
	v_lshlrev_b32_e32 v132, 1, v122
	s_mov_b32 s43, 0xbfb8aa3b
	s_mov_b32 s44, 0x3d800000
	v_mbcnt_hi_u32_b32 v133, -1, v2
	s_mov_b32 s22, s2
	s_branch .LBB0_1042

; __device__ __forceinline__ void xcd_barrier(const XcdBarrier& b) {
;     asm volatile("s_waitcnt vmcnt(0)" ::: "memory");
;     __syncthreads();
;     if (threadIdx.x == 0) {
;         unsigned* bar = b.bar;
;         __builtin_amdgcn_s_waitcnt(0);
;         unsigned nloc = b.st[0], nx = b.st[1];
;         if (nloc == 0u) { xcd_barrier_complete(bar, b.x, nloc, nx); b.st[0] = nloc; b.st[1] = nx; }
.LBB0_1195:
	v_readlane_b32 s0, v252, 28
	v_readlane_b32 s1, v252, 29
	s_cmp_gt_i32 s1, 5
	s_cselect_b64 s[0:1], -1, 0
	s_and_b64 s[4:5], s[20:21], s[0:1]
	s_andn2_b64 vcc, exec, s[4:5]
	s_cbranch_vccnz .LBB0_1245
	s_waitcnt vmcnt(0) lgkmcnt(0)
	s_barrier
	v_readfirstlane_b32 s98, v0
	s_cmp_lg_u32 s98, 0
	s_cbranch_scc1 .Lxb4_end
	s_mov_b64 s[100:101], exec
	v_readlane_b32 s98, v253, 0
	s_cmp_lg_u32 s98, 0
	s_cbranch_scc1 .Lxb4_have
	s_mov_b64 exec, 0xffff
	v_mbcnt_lo_u32_b32 v254, -1, 0
	v_lshlrev_b32_e32 v254, 8, v254
	s_mov_b32 s99, 0
	v_writelane_b32 v253, s99, 3

; __global__ void __launch_bounds__(NTHREADS, 2) fwd_kernel(Params P) {
;     ...
;     if (IN(5)) {
;         for (int gid = bx * NTHREADS + tid; gid < 16 * 8192; gid += G * NTHREADS) {
;             const int bh = gid >> 13, e = gid & 8191, k = e >> 6;
;             f32x4 ds[15]; float dd[15];
; #pragma unroll
;             for (int j = 0; j < 15; ++j) { ds[j] = *((const f32x4*)(DS + (size_t)(bh * 15 + j) * 32768) + e); dd[j] = DV[(size_t)(bh * 15 + j) * 128 + k]; }
.Lxb4_end:
	s_barrier
.LBB0_1245:
	v_readlane_b32 s4, v252, 28
	v_readlane_b32 s5, v252, 29
	s_cmp_lt_i32 s4, 6
	s_cselect_b64 s[4:5], -1, 0
	s_and_b64 s[4:5], s[4:5], s[0:1]
	s_andn2_b64 vcc, exec, s[4:5]
	s_cbranch_vccnz .LBB0_1250
	s_waitcnt vmcnt(0)
	v_lshl_or_b32 v4, s2, 9, v0
	s_mov_b32 s0, 0x20000
	v_cmp_gt_i32_e32 vcc, s0, v4
	s_and_saveexec_b64 s[0:1], vcc
	s_cbranch_execz .LBB0_1249
	s_lshl_b32 s3, s71, 9
	s_mov_b64 s[6:7], 0
	s_waitcnt lgkmcnt(0)
	v_mov_b32_e32 v3, 0
	s_mov_b32 s10, 0x1ffff

; __device__ __forceinline__ void xcd_barrier(const XcdBarrier& b) {
;     asm volatile("s_waitcnt vmcnt(0)" ::: "memory");
;     __syncthreads();
;     if (threadIdx.x == 0) {
;         unsigned* bar = b.bar;
;         __builtin_amdgcn_s_waitcnt(0);
;         unsigned nloc = b.st[0], nx = b.st[1];
;         if (nloc == 0u) { xcd_barrier_complete(bar, b.x, nloc, nx); b.st[0] = nloc; b.st[1] = nx; }
.LBB0_1250:
	v_readlane_b32 s0, v252, 28
	v_readlane_b32 s1, v252, 29
	s_cmp_gt_i32 s1, 6
	s_cselect_b64 s[0:1], -1, 0
	s_and_b64 s[4:5], s[4:5], s[0:1]
	s_andn2_b64 vcc, exec, s[4:5]
	s_cbranch_vccnz .LBB0_1300
	s_waitcnt vmcnt(0) lgkmcnt(0)
	s_barrier
	v_readfirstlane_b32 s98, v0
	s_cmp_lg_u32 s98, 0
	s_cbranch_scc1 .Lxb5_end
	s_mov_b64 s[100:101], exec
	v_readlane_b32 s98, v253, 0
	s_cmp_lg_u32 s98, 0
	s_cbranch_scc1 .Lxb5_have
	s_mov_b64 exec, 0xffff
	v_mbcnt_lo_u32_b32 v254, -1, 0
	v_lshlrev_b32_e32 v254, 8, v254
	s_mov_b32 s99, 0
	v_writelane_b32 v253, s99, 3

; template <bool FULL, bool PARTIAL  > ...
;     const int tid = threadIdx.x, lane = tid & 63, r = lane & 31, h = lane >> 5; const int w = __builtin_amdgcn_readfirstlane(tid >> 6);
;     const int kt = w & 3, tt = w >> 2, kk = 32 * kt + r;
;     const int nvalid = PARTIAL ? nvalid_ : 64;
;     LAS bf16_t* QS = (LAS bf16_t*)(lds + OFF_QS); LAS bf16_t* KS = (LAS bf16_t*)(lds + OFF_KS); LAS bf16_t* KdT = (LAS bf16_t*)(lds + OFF_KDT); LAS bf16_t* Ab = (LAS bf16_t*)(lds + OFF_A);
;     LAS bf16_t* VS = (LAS bf16_t*)(lds + OFF_VS); LAS float* GAs = (LAS float*)(lds + OFF_GA); LAS float* EB = (LAS float*)(lds + OFF_EB); LAS float* CS = (LAS float*)(lds + OFF_CS);
;     LAS float* PART = (LAS float*)(lds + OFF_PART);
;     float wal[8];
; #pragma unroll
;     for (int i = 0; i < 8; ++i) wal[i] = w_alpha[(2 * i + h) * 512 + hd * 128 + kk];
;     const float bal = b_alpha[hd * 128 + kk];
;     f32x16 Sacc[4];
;     float dsum = 0.f;
;     if (FULL && tid < 256) ((LAS float*)(lds + OFF_HN))[tid] = head_norm[tid];
;     f32x4 raw_ga; u32x4 raw_k[2], raw_q[2];
;     const int nv1 = nvalid - 1;
;     const u32x4 z4 = (u32x4){0u, 0u, 0u, 0u};
;     ...
;     GLA_FETCH_KG(0);
;     asm volatile("" :: "v"(raw_ga), "v"(raw_k[0]), "v"(raw_k[1]));
;     if (FULL) asm volatile("" :: "v"(raw_q[0]), "v"(raw_q[1]));
;     if (FULL && S0) {
;         const float* s0p = S0 + (size_t)(4 * h) * 256 + 32 * w + r;
; #pragma unroll
;         for (int kb = 0; kb < 4; ++kb)
; #pragma unroll
;             for (int i = 0; i < 16; ++i) Sacc[kb][i] = s0p[(32 * kb + (i & 3) + 8 * (i >> 2)) * 256];
;     } else {
; #pragma unroll
;         for (int kb = 0; kb < 4; ++kb)
; #pragma unroll
;             for (int i = 0; i < 16; ++i) Sacc[kb][i] = 0.f;
;     }
;     f32x16 oT[2]; u32x2 grv[2][4];
;     const LAS float* hn_r = opq((LAS float*)(lds + OFF_HN) + 32 * w + 4 * h);
;     LAS float* part_p = opq(PART + r);
; __global__ void __launch_bounds__(NTHREADS, 2) fwd_kernel(Params P) {
;     ...
;         for (int it = bx; it < 256; it += G) { const int bh = it >> 4, sc = it & 15, b = bh >> 2, hd = bh & 3;
;             gla::span<true, false>(lds, b * SEQ + sc * 256, 4, 64, hd, QK, Vb, AB, GA, P.in[10], P.in[11], P.in[12], sc ? DS + (size_t)(bh * 15 + sc - 1) * 32768 : nullptr,
;                             sc == 15 ? out + OUT_GP + (size_t)bh * 32768 : nullptr, nullptr); }
.Lxb5_end:
	s_barrier
.LBB0_1300:
	v_readlane_b32 s4, v252, 28
	v_readlane_b32 s5, v252, 29
	s_cmp_lt_i32 s4, 7
	s_cselect_b64 s[4:5], -1, 0
	s_and_b64 s[4:5], s[4:5], s[0:1]
	s_cmpk_lt_i32 s2, 0x100
	s_cselect_b64 s[76:77], -1, 0
	s_and_b64 s[0:1], s[4:5], s[76:77]
	s_andn2_b64 vcc, exec, s[0:1]
	s_movk_i32 s0, 0x100
	s_cbranch_vccnz .LBB0_1332
	v_writelane_b32 v252, s4, 36
	s_add_u32 s3, s50, 0x4200000
	s_waitcnt vmcnt(0)
	v_lshrrev_b32_e32 v5, 5, v198
	v_writelane_b32 v252, s5, 37
	s_addc_u32 s33, s51, 0
	v_and_b32_e32 v162, 31, v0
	v_lshlrev_b32_e32 v2, 2, v0
	s_waitcnt lgkmcnt(0)
	v_mov_b32_e32 v3, 0
	s_add_i32 s4, 0, 0x1a700
	v_lshlrev_b32_e32 v7, 4, v5
	v_lshrrev_b32_e32 v6, 4, v0
	s_movk_i32 s86, 0x110
	v_lshlrev_b32_e32 v9, 4, v0
	v_lshl_add_u64 v[164:165], s[60:61], 0, v[2:3]
	v_add_u32_e32 v216, s4, v2
	v_add_u32_e32 v218, s4, v7
	s_add_i32 s4, 0, 0x19f00
	v_lshlrev_b32_e32 v8, 2, v162
	v_mad_u32_u24 v6, v6, s86, 0
	v_and_b32_e32 v10, 0xf0, v9
	s_movk_i32 s87, 0x4400
	v_and_b32_e32 v2, 12, v2
	v_add_u32_e32 v219, s4, v8
	v_add3_u32 v220, v6, v10, s87
	v_mul_u32_u24_e32 v6, 0x110, v2
	s_add_i32 s4, 0, 0x18400
	v_and_b32_e32 v13, 0x1fc, v0
	v_add3_u32 v221, s4, v6, v13
	v_mul_u32_u24_e32 v13, 0x110, v5
	v_add3_u32 v222, s4, v13, v8
	v_lshrrev_b32_e32 v8, 5, v0
	s_movk_i32 s6, 0x240
	v_lshlrev_b32_e32 v10, 3, v5
	v_lshrrev_b32_e32 v12, 2, v0
	v_mad_u32_u24 v8, v8, s6, 0
	v_and_b32_e32 v9, 0x1f0, v9
	s_mov_b32 s7, 0xf400
	v_add3_u32 v223, v8, v9, s7
	v_and_or_b32 v8, v12, 3, v10
	v_and_b32_e32 v9, 16, v0
	v_mad_u32_u24 v8, v8, s6, 0
	v_lshlrev_b32_e32 v9, 1, v9
	v_lshlrev_b32_e32 v2, 1, v2
	v_add3_u32 v226, v8, v9, v2
	v_mul_u32_u24_e32 v2, 0x48, v162
	v_lshlrev_b32_e32 v217, 2, v5
	v_lshlrev_b32_e32 v2, 1, v2
	v_lshl_or_b32 v6, v162, 11, v217
	v_add3_u32 v2, 0, v2, v7
	v_add_u32_e32 v227, 0xd000, v2
	v_add_u32_e32 v228, 0x8800, v2
	v_lshlrev_b32_e32 v2, 1, v6
	v_lshlrev_b32_e32 v4, 10, v5
	v_add_u32_e32 v11, 0, v10
	s_add_i32 s88, 0, 0x19500
	v_lshl_add_u64 v[168:169], s[68:69], 0, v[2:3]
	v_mbcnt_lo_u32_b32 v2, -1, 0
	v_writelane_b32 v252, s76, 3
	v_lshlrev_b32_e32 v163, 9, v5
	v_cmp_gt_u32_e64 s[0:1], s0, v0
	s_mov_b32 s61, 0
	v_cmp_gt_u32_e64 s[4:5], 32, v198
	v_add_u32_e32 v224, v11, v10
	v_mad_u32_u24 v225, v162, s86, v11
	v_add_u32_e32 v229, s88, v7
	v_lshlrev_b32_e32 v166, 12, v5
	v_mov_b32_e32 v167, v3
	s_lshl_b32 s89, s2, 6
	s_lshl_b32 s42, s71, 6
	v_lshlrev_b32_e32 v170, 2, v4
	s_add_i32 s43, 0, 0x19700
	v_lshlrev_b32_e32 v172, 1, v6
	v_mov_b32_e32 v230, 0x358637bd
	s_mov_b32 s44, 0xbfb8aa3b
	s_mov_b32 s45, 0x3d800000
	v_lshlrev_b32_e32 v174, 2, v162
	v_mbcnt_hi_u32_b32 v231, -1, v2
	s_mov_b32 s78, s2
	s_mov_b32 s79, s2
	v_writelane_b32 v252, s77, 4
	s_branch .LBB0_1303

; __device__ __forceinline__ void xcd_barrier(const XcdBarrier& b) {
;     asm volatile("s_waitcnt vmcnt(0)" ::: "memory");
;     __syncthreads();
;     if (threadIdx.x == 0) {
;         unsigned* bar = b.bar;
;         __builtin_amdgcn_s_waitcnt(0);
;         unsigned nloc = b.st[0], nx = b.st[1];
;         if (nloc == 0u) { xcd_barrier_complete(bar, b.x, nloc, nx); b.st[0] = nloc; b.st[1] = nx; }
.LBB0_1332:
	v_readlane_b32 s84, v252, 28
	v_readlane_b32 s85, v252, 29
	s_cmp_gt_i32 s85, 7
	s_cselect_b64 s[0:1], -1, 0
	s_and_b64 s[4:5], s[4:5], s[0:1]
	s_andn2_b64 vcc, exec, s[4:5]
	s_cbranch_vccnz .LBB0_1382
	s_waitcnt vmcnt(0) lgkmcnt(0)
	s_barrier
	v_readfirstlane_b32 s98, v0
	s_cmp_lg_u32 s98, 0
	s_cbranch_scc1 .Lxb6_end
	s_mov_b64 s[100:101], exec
	v_readlane_b32 s98, v253, 0
	s_cmp_lg_u32 s98, 0
	s_cbranch_scc1 .Lxb6_have
	s_mov_b64 exec, 0xffff
	v_mbcnt_lo_u32_b32 v254, -1, 0
	v_lshlrev_b32_e32 v254, 8, v254
	s_mov_b32 s99, 0
	v_writelane_b32 v253, s99, 3

; __global__ void __launch_bounds__(NTHREADS, 2) fwd_kernel(Params P) {
;     ...
;     if (IN(7)) {
;         pg8::Gemm g{AB, Wbr, 2048, 2048, D, 1024}; pg8::Sched S; S.init(MP, D, G, bx, 1);
;         pg8::EpiMerge E{Gb, Gb, 0x7fffffff};
;         skinny::EpiMerge Es{Gb};
;         if (sk_early) skinny::phase<2, D / 256, false>(lds, AB, 2048, Wbr, 2048, 1024, nullptr, G, sk_piece, Es);
;         pg8::gemm_phase(lds, g, S, E);
;         if (!sk_early) skinny::phase<2, D / 256, false>(lds, AB, 2048, Wbr, 2048, 1024, nullptr, G, sk_piece, Es);
.Lxb6_end:
	s_barrier
.LBB0_1382:
	s_cmp_lt_i32 s84, 8
	s_cselect_b64 s[4:5], -1, 0
	s_and_b64 s[8:9], s[4:5], s[0:1]
	s_andn2_b64 vcc, exec, s[8:9]
	s_cbranch_vccnz .LBB0_1493
	v_readlane_b32 s4, v252, 18
	v_readlane_b32 s5, v252, 19
	s_andn2_b64 vcc, exec, s[4:5]
	s_waitcnt vmcnt(0)
	v_cndmask_b32_e64 v2, 0, 1, s[4:5]
	v_cmp_ne_u32_e64 s[0:1], 1, v2
	s_cbranch_vccnz .LBB0_1385
	v_lshrrev_b32_e32 v223, 2, v0
	v_and_b32_e32 v222, 15, v0
	s_cbranch_execz .LBB0_1386
	s_branch .LBB0_1393

; __device__ __forceinline__ void xcd_barrier(const XcdBarrier& b) {
;     asm volatile("s_waitcnt vmcnt(0)" ::: "memory");
;     __syncthreads();
;     if (threadIdx.x == 0) {
;         unsigned* bar = b.bar;
;         __builtin_amdgcn_s_waitcnt(0);
;         unsigned nloc = b.st[0], nx = b.st[1];
;         if (nloc == 0u) { xcd_barrier_complete(bar, b.x, nloc, nx); b.st[0] = nloc; b.st[1] = nx; }
.LBB0_1493:
	s_cmp_gt_i32 s85, 8
	s_cselect_b64 s[0:1], -1, 0
	s_and_b64 s[4:5], s[8:9], s[0:1]
	s_andn2_b64 vcc, exec, s[4:5]
	s_cbranch_vccnz .LBB0_1543
	s_waitcnt vmcnt(0) lgkmcnt(0)
	s_barrier
	v_readfirstlane_b32 s98, v0
	s_cmp_lg_u32 s98, 0
	s_cbranch_scc1 .Lxb7_end
	s_mov_b64 s[100:101], exec
	v_readlane_b32 s98, v253, 0
	s_cmp_lg_u32 s98, 0
	s_cbranch_scc1 .Lxb7_have
	s_mov_b64 exec, 0xffff
	v_mbcnt_lo_u32_b32 v254, -1, 0
	v_lshlrev_b32_e32 v254, 8, v254
	s_mov_b32 s99, 0
	v_writelane_b32 v253, s99, 3

; __global__ void __launch_bounds__(NTHREADS, 2) fwd_kernel(Params P) {
;     ...
;     if (IN(8)) {
;         pg8::Gemm g{Gb, Wout, 2048, D, D, 0}; pg8::Sched S; S.init(MP, D, G, bx, 0);
;         pg8::EpiResidual<true, false, true> E{XA, nullptr, nullptr, QK, ssq2, 1.0f};
;         skinny::EpiResidual<true, false, true> Es{XA, nullptr, QK, 1.0f};
;         if (sk_early) skinny::phase<1, D / 256, false>(lds, Gb, 2048, Wout, D, 0, ssq2, G, sk_piece, Es);
;         pg8::gemm_phase(lds, g, S, E);
;         if (!sk_early) skinny::phase<1, D / 256, false>(lds, Gb, 2048, Wout, D, 0, ssq2, G, sk_piece, Es);
.Lxb7_end:
	s_barrier
.LBB0_1543:
	s_cmp_lt_i32 s84, 9
	s_cselect_b64 s[4:5], -1, 0
	s_add_u32 s10, s68, 0x218000
	s_addc_u32 s11, s69, 0
	s_and_b64 s[12:13], s[4:5], s[0:1]
	s_andn2_b64 vcc, exec, s[12:13]
	s_cbranch_vccnz .LBB0_1608
	v_readlane_b32 s4, v252, 18
	v_readlane_b32 s5, v252, 19
	s_andn2_b64 vcc, exec, s[4:5]
	s_waitcnt vmcnt(0)
	v_cndmask_b32_e64 v2, 0, 1, s[4:5]
	v_cmp_ne_u32_e64 s[0:1], 1, v2
	s_cbranch_vccnz .LBB0_1546
	v_lshrrev_b32_e32 v208, 2, v0
	v_and_b32_e32 v195, 15, v0
	s_cbranch_execz .LBB0_1547
	s_branch .LBB0_1556

; __device__ __forceinline__ void xcd_barrier(const XcdBarrier& b) {
;     asm volatile("s_waitcnt vmcnt(0)" ::: "memory");
;     __syncthreads();
;     if (threadIdx.x == 0) {
;         unsigned* bar = b.bar;
;         __builtin_amdgcn_s_waitcnt(0);
;         unsigned nloc = b.st[0], nx = b.st[1];
;         if (nloc == 0u) { xcd_barrier_complete(bar, b.x, nloc, nx); b.st[0] = nloc; b.st[1] = nx; }
.LBB0_1608:
	s_cmp_gt_i32 s85, 9
	s_cselect_b64 s[0:1], -1, 0
	s_and_b64 s[4:5], s[12:13], s[0:1]
	s_andn2_b64 vcc, exec, s[4:5]
	v_readlane_b32 s82, v252, 26
	v_readlane_b32 s83, v252, 27
	s_cbranch_vccnz .LBB0_1658
	s_waitcnt vmcnt(0) lgkmcnt(0)
	s_barrier
	v_readfirstlane_b32 s98, v0
	s_cmp_lg_u32 s98, 0
	s_cbranch_scc1 .Lxb8_end
	s_mov_b64 s[100:101], exec
	v_readlane_b32 s98, v253, 0
	s_cmp_lg_u32 s98, 0
	s_cbranch_scc1 .Lxb8_have
	s_mov_b64 exec, 0xffff
	v_mbcnt_lo_u32_b32 v254, -1, 0
	v_lshlrev_b32_e32 v254, 8, v254
	s_mov_b32 s99, 0
	v_writelane_b32 v253, s99, 3

;     __device__ __forceinline__ bool next(int i, Unit& u) const {
;         const long L = (long)(i >> psh) * G + c; if (L >= nwg) return false;
;         int wgid = (int)L; { const int q = nwg / NXCD, r = nwg % NXCD, xcd = wgid % NXCD, off = wgid / NXCD; wgid = (xcd < r ? xcd * (q + 1) : r * (q + 1) + (xcd - r) * q) + off; }
;         const int nig = WGM * nN, gid = wgid / nig, fm = gid * WGM, gsz = (nM - fm) < WGM ? (nM - fm) : WGM;
;         u.pm = fm + ((wgid % nig) % gsz); u.pn = (wgid % nig) / gsz; u.part = i & ((1 << psh) - 1); u.idx = i; return true;
; __global__ void __launch_bounds__(NTHREADS, 2) fwd_kernel(Params P) {
;     ...
;     if (IN(9)) {
;         pg8::Gemm g{QK, Wup2, D, D, D, 0}; pg8::Sched S; S.init(M, NUP, G, bx, 0);
;         RSTD_TABLE_FILL(S, ssq2, false);
.Lxb8_end:
	s_barrier
.LBB0_1658:
	s_cmp_lt_i32 s84, 10
	s_cselect_b64 s[4:5], -1, 0
	s_and_b64 s[12:13], s[4:5], s[0:1]
	s_andn2_b64 vcc, exec, s[12:13]
	s_cbranch_vccnz .LBB0_1725
	s_ashr_i32 s3, s2, 31
	s_waitcnt vmcnt(0) lgkmcnt(0)
	v_mov_b64_e32 v[2:3], s[2:3]
	v_mad_i64_i32 v[2:3], s[0:1], v199, s71, v[2:3]
	s_mov_b64 s[0:1], 0x596
	s_ashr_i32 s28, s71, 31
	v_cmp_gt_i64_e32 vcc, s[0:1], v[2:3]
	v_mov_b32_e32 v3, 0
	s_and_saveexec_b64 s[4:5], vcc
	s_cbranch_execz .LBB0_1665
	v_ashrrev_i32_e32 v3, 31, v2
	v_lshrrev_b32_e32 v3, 29, v3
	v_add_u32_e32 v4, v2, v3
	v_and_b32_e32 v3, -8, v4
	v_sub_u32_e32 v3, v2, v3
	v_cmp_lt_i32_e64 s[0:1], 5, v3
	s_and_saveexec_b64 s[6:7], s[0:1]
	s_xor_b64 s[0:1], exec, s[6:7]
	s_movk_i32 s6, 0xb2
	v_mad_u64_u32 v[2:3], s[6:7], v3, s6, 6
	s_or_saveexec_b64 s[0:1], s[0:1]
	v_ashrrev_i32_e32 v4, 3, v4
	s_xor_b64 exec, exec, s[0:1]
	s_movk_i32 s6, 0xb3
	v_mul_lo_u32 v2, v3, s6
	s_or_b64 exec, exec, s[0:1]
	v_add_u32_e32 v2, v2, v4
	s_mov_b32 s0, 0x2e8ba2e9
	v_mul_hi_i32 v3, v2, s0
	v_lshrrev_b32_e32 v4, 31, v3
	v_ashrrev_i32_e32 v3, 4, v3
	v_add_u32_e32 v3, v3, v4
	v_lshlrev_b32_e32 v4, 2, v3
	v_sub_u32_e32 v5, 0x41, v4
	v_min_i32_e32 v5, 4, v5
	v_sub_u32_e32 v6, 0, v5
	v_max_i32_e32 v5, v5, v6
	v_cvt_f32_u32_e32 v6, v5
	s_movk_i32 s0, 0x58
	v_mul_lo_u32 v3, v3, s0
	v_sub_u32_e32 v2, v2, v3
	v_rcp_iflag_f32_e32 v6, v6
	v_sub_u32_e32 v7, 0, v2
	v_ashrrev_i32_e32 v3, 31, v2
	v_max_i32_e32 v2, v2, v7
	v_mul_f32_e32 v6, 0x4f7ffffe, v6
	v_cvt_u32_f32_e32 v6, v6
	v_sub_u32_e32 v7, 0, v5
	v_mul_lo_u32 v7, v7, v6
	v_mul_hi_u32 v7, v6, v7
	v_add_u32_e32 v6, v6, v7
	v_mul_hi_u32 v6, v2, v6
	v_mul_lo_u32 v6, v6, v5
	v_sub_u32_e32 v2, v2, v6
	v_sub_u32_e32 v6, v2, v5
	v_cmp_ge_u32_e64 s[0:1], v2, v5
	s_nop 1
	v_cndmask_b32_e64 v2, v2, v6, s[0:1]
	v_sub_u32_e32 v6, v2, v5
	v_cmp_ge_u32_e64 s[0:1], v2, v5
	s_nop 1
	v_cndmask_b32_e64 v2, v2, v6, s[0:1]
	v_xor_b32_e32 v2, v2, v3
	v_sub_u32_e32 v2, v2, v3
	v_add_lshl_u32 v3, v4, v2, 8

; __device__ __forceinline__ void xcd_barrier(const XcdBarrier& b) {
;     asm volatile("s_waitcnt vmcnt(0)" ::: "memory");
;     __syncthreads();
;     if (threadIdx.x == 0) {
;         unsigned* bar = b.bar;
;         __builtin_amdgcn_s_waitcnt(0);
;         unsigned nloc = b.st[0], nx = b.st[1];
;         if (nloc == 0u) { xcd_barrier_complete(bar, b.x, nloc, nx); b.st[0] = nloc; b.st[1] = nx; }
.LBB0_1725:
	s_cmp_gt_i32 s85, 10
	s_cselect_b64 s[0:1], -1, 0
	s_and_b64 s[4:5], s[12:13], s[0:1]
	s_andn2_b64 vcc, exec, s[4:5]
	s_cbranch_vccnz .LBB0_1775
	s_waitcnt vmcnt(0) lgkmcnt(0)
	s_barrier
	v_readfirstlane_b32 s98, v0
	s_cmp_lg_u32 s98, 0
	s_cbranch_scc1 .Lxb9_end
	s_mov_b64 s[100:101], exec
	v_readlane_b32 s98, v253, 0
	s_cmp_lg_u32 s98, 0
	s_cbranch_scc1 .Lxb9_have
	s_mov_b64 exec, 0xffff
	v_mbcnt_lo_u32_b32 v254, -1, 0
	v_lshlrev_b32_e32 v254, 8, v254
	s_mov_b32 s99, 0
	v_writelane_b32 v253, s99, 3

; __global__ void __launch_bounds__(NTHREADS, 2) fwd_kernel(Params P) {
;     ...
;     const bool fuse_final = (G == 256) && IN(10) && IN(11);
;     if (IN(10)) {
;         pg8::Gemm g{Hb, Wdn2, FF, FF, FF, 0}; pg8::Sched S; S.init(MP, D, G, bx, 0);
;         unsigned* xcnt = (unsigned*)(ws + WS_CTL) + 4096;
;         if (fuse_final) {
;             pg8::EpiFinal E{QK, out + OUT_Y, P.in[22], ssq3, xcnt, 0.5f};
;             skinny::EpiResidual<true, false, false> Es{QK, nullptr, nullptr, 0.5f};
;             if (sk_early) skinny::phase<1, FF / 256, true>(lds, Hb, FF, Wdn2, FF, 0, ssq3, G, sk_piece, Es, P.in[22], out + OUT_Y, xcnt + 64 * 64);
;             pg8::gemm_phase(lds, g, S, E);
;             if (!sk_early) { __syncthreads();
;                 skinny::phase<1, FF / 256, true>(lds, Hb, FF, Wdn2, FF, 0, ssq3, G, sk_piece, Es, P.in[22], out + OUT_Y, xcnt + 64 * 64); }
.Lxb9_end:
	s_barrier
.LBB0_1775:
	s_cmp_lt_i32 s84, 11
	v_readlane_b32 s4, v252, 21
	s_cselect_b64 s[6:7], -1, 0
	v_readlane_b32 s5, v252, 22
	s_and_b64 s[4:5], s[6:7], s[4:5]
	s_cmp_gt_i32 s85, 11
	s_cselect_b64 s[10:11], -1, 0
	s_and_b64 s[16:17], s[4:5], s[10:11]
	s_and_b64 s[0:1], s[6:7], s[0:1]
	s_mov_b64 s[4:5], -1
	s_xor_b64 s[18:19], s[16:17], -1
	s_andn2_b64 vcc, exec, s[0:1]
	s_mov_b64 s[0:1], 0
	s_cbranch_vccnz .LBB0_1961
	s_add_u32 s20, s68, 0x31c000
	s_waitcnt vmcnt(0)
	v_cndmask_b32_e64 v2, 0, 1, s[76:77]
	s_addc_u32 s21, s69, 0
	s_and_b64 vcc, exec, s[18:19]
	v_cmp_ne_u32_e64 s[0:1], 1, v2
	s_cbranch_vccz .LBB0_1833
	s_and_b64 vcc, exec, s[0:1]
	v_readfirstlane_b32 s6, v0
	s_cbranch_vccnz .LBB0_1783
	s_ashr_i32 s3, s2, 31
	s_lshr_b32 s3, s3, 29
	s_add_i32 s8, s2, s3
	s_and_b32 s3, s8, -8
	s_sub_i32 s3, s2, s3
	s_cmp_gt_i32 s3, -1
	s_cbranch_scc0 .LBB0_1780
	s_lshl_b32 s7, s3, 5
	s_ashr_i32 s4, s8, 3
	s_cbranch_execz .LBB0_1781
	s_branch .LBB0_1782

; __global__ void __launch_bounds__(NTHREADS, 2) fwd_kernel(Params P) {
	.amdhsa_kernel _Z10fwd_kernel6Params
		.amdhsa_group_segment_fixed_size 0
		.amdhsa_private_segment_fixed_size 0
		.amdhsa_kernarg_size 464
		.amdhsa_user_sgpr_count 2
		.amdhsa_user_sgpr_dispatch_ptr 0
		.amdhsa_user_sgpr_queue_ptr 0
		.amdhsa_user_sgpr_kernarg_segment_ptr 1
		.amdhsa_user_sgpr_dispatch_id 0
		.amdhsa_user_sgpr_kernarg_preload_length 0
		.amdhsa_user_sgpr_kernarg_preload_offset 0
		.amdhsa_user_sgpr_private_segment_size 0
		.amdhsa_uses_dynamic_stack 0
		.amdhsa_enable_private_segment 0
		.amdhsa_system_sgpr_workgroup_id_x 1
		.amdhsa_system_sgpr_workgroup_id_y 0
		.amdhsa_system_sgpr_workgroup_id_z 0
		.amdhsa_system_sgpr_workgroup_info 0
		.amdhsa_system_vgpr_workitem_id 0
		.amdhsa_next_free_vgpr 256
		.amdhsa_next_free_sgpr 102
		.amdhsa_accum_offset 256
		.amdhsa_reserve_vcc 1
		.amdhsa_float_round_mode_32 0
		.amdhsa_float_round_mode_16_64 0
		.amdhsa_float_denorm_mode_32 3
		.amdhsa_float_denorm_mode_16_64 3
		.amdhsa_dx10_clamp 1
		.amdhsa_ieee_mode 1
		.amdhsa_fp16_overflow 0
		.amdhsa_tg_split 0
		.amdhsa_exception_fp_ieee_invalid_op 0
		.amdhsa_exception_fp_denorm_src 0
		.amdhsa_exception_fp_ieee_div_zero 0
		.amdhsa_exception_fp_ieee_overflow 0
		.amdhsa_exception_fp_ieee_underflow 0
		.amdhsa_exception_fp_ieee_inexact 0
		.amdhsa_exception_int_div_zero 0
	.end_amdhsa_kernel

; __global__ void __launch_bounds__(NTHREADS, 2) fwd_kernel(Params P) {
amdhsa.kernels:
  - .agpr_count:     0
    .args:
      - .offset:         0
        .size:           208
        .value_kind:     by_value
      - .offset:         208
        .size:           4
        .value_kind:     hidden_block_count_x
      - .offset:         212
        .size:           4
        .value_kind:     hidden_block_count_y
      - .offset:         216
        .size:           4
        .value_kind:     hidden_block_count_z
      - .offset:         220
        .size:           2
        .value_kind:     hidden_group_size_x
      - .offset:         222
        .size:           2
        .value_kind:     hidden_group_size_y
      - .offset:         224
        .size:           2
        .value_kind:     hidden_group_size_z
      - .offset:         226
        .size:           2
        .value_kind:     hidden_remainder_x
      - .offset:         228
        .size:           2
        .value_kind:     hidden_remainder_y
      - .offset:         230
        .size:           2
        .value_kind:     hidden_remainder_z
      - .offset:         248
        .size:           8
        .value_kind:     hidden_global_offset_x
      - .offset:         256
        .size:           8
        .value_kind:     hidden_global_offset_y
      - .offset:         264
        .size:           8
        .value_kind:     hidden_global_offset_z
      - .offset:         272
        .size:           2
        .value_kind:     hidden_grid_dims
      - .offset:         328
        .size:           4
        .value_kind:     hidden_dynamic_lds_size
    .group_segment_fixed_size: 0
    .kernarg_segment_align: 8
    .kernarg_segment_size: 464
    .language:       OpenCL C
    .language_version:
      - 2
      - 0
    .max_flat_workgroup_size: 512
    .name:           _Z10fwd_kernel6Params
    .private_segment_fixed_size: 0
    .sgpr_count:     108
    .sgpr_spill_count: 56
    .symbol:         _Z10fwd_kernel6Params.kd
    .uniform_work_group_size: 1
    .uses_dynamic_stack: false
    .vgpr_count:     256
    .vgpr_spill_count: 0
    .wavefront_size: 64
